# out-proj: workgroups owning a context half tile process it before their 256x128 tile instead of after (same tiles and code, order only)
# speedup vs baseline: 1.0008x; 1.0008x over previous
; DI void outproj_phase(const Params& p, int l, char* smem) {
;     constexpr int NT = 8, MT = NTOK / 128;
;     const bool xmap = gridDim.x == 512;
;     const int xcd = blockIdx.x & 7, xj = blockIdx.x >> 3;
;     const bool ctxu = l < DEPTH - 1;
;     if (xmap) {
; #pragma unroll 1
;         for (int it = 0; it < 2; ++it) { const int idx = it * 64 + xj; outproj_tile<2>(p, l, smem, xcd, (idx >> 3) * 128, (idx & 7) * 128); }
;         if (ctxu && xj < 32) { const int tile = xj >> 1; outproj_tile<1>(p, l, smem, xcd, SEQ + (tile >> 3) * 128 + (xj & 1) * 64, (tile & 7) * 128); }
.LBB0_35:
	s_andn2_b64 vcc, exec, s[4:5]
	s_cbranch_vccnz .LBB0_68
	s_mov_b32 s99, 0
.Lop_main_setup:
	s_ashr_i32 s61, s60, 31
	s_lshl_b64 s[58:59], s[60:61], 21
	v_readlane_b32 s4, v255, 34
	v_readlane_b32 s5, v255, 35
	s_cmp_gt_u32 s4, 4
	s_movk_i32 s61, 0x800
	s_cselect_b64 s[50:51], -1, 0
	s_mov_b32 s6, 0
	s_mov_b64 s[4:5], -1
	s_cmp_eq_u32 s99, 2
	s_cbranch_scc1 .LBB0_39
	s_mov_b32 s99, 1
	s_load_dwordx2 s[8:9], s[0:1], 0xd8
	s_load_dwordx2 s[56:57], s[0:1], 0xb8
	s_load_dwordx4 s[44:47], s[0:1], 0xa8
	s_load_dwordx2 s[52:53], s[0:1], 0xe0
	s_waitcnt lgkmcnt(0)
	s_add_u32 s8, s8, s58
	s_addc_u32 s9, s9, s59
	s_branch .LBB0_52

; DI void outproj_phase(const Params& p, int l, char* smem) {
;     ...
;         for (int it = 0; it < 2; ++it) { const int idx = it * 64 + xj; outproj_tile<2>(p, l, smem, xcd, (idx >> 3) * 128, (idx & 7) * 128); }
;         if (ctxu && xj < 32) { const int tile = xj >> 1; outproj_tile<1>(p, l, smem, xcd, SEQ + (tile >> 3) * 128 + (xj & 1) * 64, (tile & 7) * 128); }
.Lop_ctx_done:
	s_cmp_eq_u32 s99, 1
	s_cbranch_scc0 .LBB0_68
	s_mov_b32 s99, 2
	s_branch .Lop_main_setup
